# three P1 classes by blockIdx%8: 0 converts weights first; 1-3 convert between the int8 and bf16 GEMM1 calls; 4-7 convert after GEMM1 (plus peel + conv fast path)
# baseline (speedup 1.0000x reference)
_Z3fwd4Args:
	v_writelane_b32 v249, s0, 0
	v_writelane_b32 v249, s1, 1
	v_writelane_b32 v249, s2, 2
	v_mov_b32_e32 v250, v0
	s_and_b32 s98, s2, 7
	s_movk_i32 s101, 0x100
	s_cmp_lt_u32 s98, 4
	s_cselect_b32 s101, 0x400, s101
	s_cmp_lt_u32 s98, 1
	s_cselect_b32 s101, 0, s101

.LBB0_189:
	v_writelane_b32 v248, s59, 41
	s_nop 0
	v_readlane_b32 s0, v248, 6
	v_readlane_b32 s2, v248, 8
	v_readlane_b32 s1, v248, 7
	v_readlane_b32 s3, v248, 9
	s_add_u32 s0, s2, 0x240000
	s_addc_u32 s1, s3, 0
	v_writelane_b32 v248, s0, 55
	s_nop 1
	v_writelane_b32 v248, s1, 56
	s_add_u32 s0, s2, 0x2c0000
	s_addc_u32 s1, s3, 0
	s_add_u32 s60, s2, 0x8800000
	s_addc_u32 s61, s3, 0
	s_add_u32 s30, s2, 0xa800000
	s_addc_u32 s31, s3, 0
	s_add_u32 s82, s2, 0xb800000
	v_writelane_b32 v248, s0, 43
	s_addc_u32 s83, s3, 0
	s_nop 0
	v_writelane_b32 v248, s1, 44
	s_add_u32 s0, s2, 0x18400000
	v_writelane_b32 v248, s0, 33
	s_addc_u32 s0, s3, 0
	s_add_u32 s14, s2, 0x22200000
	s_addc_u32 s15, s3, 0
	v_writelane_b32 v248, s0, 47
	s_add_u32 s0, s2, 0x24600000
	s_addc_u32 s1, s3, 0
	v_writelane_b32 v248, s0, 45
	s_nop 1
	v_writelane_b32 v248, s1, 46
	s_add_u32 s0, s2, 0x26a00000
	s_addc_u32 s1, s3, 0
	s_add_u32 s56, s2, 0x28e00000
	s_addc_u32 s57, s3, 0
	s_add_u32 s58, s2, 0x2d600000
	s_addc_u32 s59, s3, 0
	s_add_u32 s48, s2, 0x540000
	v_writelane_b32 v248, s0, 49
	s_addc_u32 s49, s3, 0
	s_nop 0
	v_writelane_b32 v248, s1, 50
	s_add_u32 s0, s2, 0xd800000
	v_writelane_b32 v248, s0, 51
	s_addc_u32 s0, s3, 0
	s_cmp_lt_i32 s4, 2
	v_writelane_b32 v248, s0, 53
	s_cselect_b64 s[0:1], -1, 0
	s_cmp_gt_i32 s5, 1
	s_cselect_b64 s[2:3], -1, 0
	s_and_b64 s[0:1], s[0:1], s[2:3]
	s_andn2_b64 vcc, exec, s[0:1]
	v_writelane_b32 v248, s82, 37
	s_nop 1
	v_writelane_b32 v248, s83, 38
	s_cbranch_vccnz .LBB0_380
	s_bfe_u32 s98, s101, 0x80008
	s_cmp_eq_u32 s98, 3
	s_cbranch_scc0 .Lcls_nobaronly
	s_and_b32 s101, s101, 0xff
	s_branch .LBB0_326
.Lcls_nobaronly:
	s_cmp_eq_u32 s98, 1
	s_cbranch_scc1 .Lcls_skipcopy
	s_cmp_eq_u32 s98, 4
	s_cbranch_scc1 .Lcls_skipcopy
	s_cmp_eq_u32 s98, 6
	s_cbranch_scc0 .Lcls_docopy
.Lcls_skipcopy:
	v_writelane_b32 v248, s96, 59
	v_writelane_b32 v248, s97, 60
	v_lshlrev_b32_e32 v1, 2, v0
	v_and_b32_e32 v130, 48, v0
	s_branch .LBB0_222

.LBB0_222:
	s_bfe_u32 s98, s101, 0x80008
	s_cmp_eq_u32 s98, 2
	s_cbranch_scc0 .Lcls_222a
	s_movk_i32 s101, 0x301
	s_mov_b64 exec, -1
	v_readlane_b32 s0, v249, 0
	v_readlane_b32 s1, v249, 1
	v_readlane_b32 s2, v249, 2
	v_mov_b32_e32 v0, v250
	s_nop 4
	s_branch .Lcls_top
.Lcls_222a:
	s_cmp_eq_u32 s98, 5
	s_cbranch_scc0 .Lcls_222b
	s_movk_i32 s101, 0x601
	s_mov_b64 exec, -1
	v_readlane_b32 s0, v249, 0
	v_readlane_b32 s1, v249, 1
	v_readlane_b32 s2, v249, 2
	v_mov_b32_e32 v0, v250
	s_nop 4
	s_branch .Lcls_top
.Lcls_222b:
	s_cmp_eq_u32 s98, 6
	s_cbranch_scc0 .Lcls_222c
	v_readlane_b32 s84, v248, 32
	s_barrier
	s_branch .Lcls_nometa

.Lcls_nometa:
	v_and_b32_e32 v169, 15, v0
	s_mov_b64 s[0:1], 0
	s_branch .LBB0_225

.LBB0_236:
	s_bfe_u32 s98, s101, 0x80008
	s_cmp_eq_u32 s98, 6
	s_cbranch_scc0 .Lcls_236a
	s_mov_b64 s[0:1], -1

.LBB0_256:
	s_bfe_u32 s98, s101, 0x80008
	s_cmp_eq_u32 s98, 4
	s_cbranch_scc0 .Lcls_256a
	s_movk_i32 s101, 0x501
	s_mov_b64 exec, -1
	v_readlane_b32 s0, v249, 0
	v_readlane_b32 s1, v249, 1
	v_readlane_b32 s2, v249, 2
	v_mov_b32_e32 v0, v250
	s_nop 4
	s_branch .Lcls_top

.LBB0_326:
	s_bfe_u32 s98, s101, 0x80008
	s_cmp_eq_u32 s98, 1
	s_cbranch_scc0 .Lcls_326a
	s_movk_i32 s101, 0x201
	s_mov_b64 exec, -1
	v_readlane_b32 s0, v249, 0
	v_readlane_b32 s1, v249, 1
	v_readlane_b32 s2, v249, 2
	v_mov_b32_e32 v0, v250
	s_nop 4
	s_branch .Lcls_top
.Lcls_326a:
	s_and_b32 s101, s101, 0xff
	v_readlane_b32 s4, v248, 4
	v_readlane_b32 s5, v248, 5
	s_cmp_gt_i32 s5, 2
	s_cbranch_scc0 .LBB0_380
	s_waitcnt vmcnt(0)
	s_waitcnt vmcnt(0) lgkmcnt(0)
	s_barrier
	s_mov_b64 s[0:1], exec
	v_readlane_b32 s2, v248, 13
	v_readlane_b32 s3, v248, 14
	s_and_b64 s[2:3], s[0:1], s[2:3]
	s_mov_b64 exec, s[2:3]
	s_cbranch_execz .LBB0_379
	s_add_i32 s2, 0, 0x23f20
	v_mov_b32_e32 v1, s2
	s_waitcnt vmcnt(0) expcnt(0) lgkmcnt(0)
	ds_read_b32 v3, v1
	s_add_i32 s2, 0, 0x23f24
	v_mov_b32_e32 v1, s2
	ds_read_b32 v1, v1
	s_waitcnt lgkmcnt(1)
	v_cmp_ne_u32_e32 vcc, 0, v3
	s_cbranch_vccnz .LBB0_343
	v_readlane_b32 s2, v248, 1
	v_readlane_b32 s3, v248, 2
	v_readlane_b32 s40, v248, 6
	s_load_dwordx2 s[6:7], s[2:3], 0x4
	v_readlane_b32 s42, v248, 8
	v_readlane_b32 s43, v248, 9
	s_add_u32 s2, s42, 0x1200
	s_addc_u32 s3, s43, 0
	s_add_u32 s4, s42, 0x1400
	s_addc_u32 s5, s43, 0
	s_waitcnt lgkmcnt(0)
	s_mul_i32 s33, s6, s95
	s_add_u32 s6, s42, 0x1500
	s_mul_i32 s33, s33, s7
	s_addc_u32 s7, s43, 0
	s_add_u32 s8, s42, 0x1600
	s_addc_u32 s9, s43, 0
	s_add_u32 s10, s42, 0x1700
	s_addc_u32 s11, s43, 0
	s_add_u32 s12, s42, 0x1800
	s_addc_u32 s13, s43, 0
	s_add_u32 s16, s42, 0x1900
	s_addc_u32 s17, s43, 0
	s_add_u32 s18, s42, 0x1a00
	s_addc_u32 s19, s43, 0
	s_add_u32 s20, s42, 0x1b00
	s_addc_u32 s21, s43, 0
	s_add_u32 s22, s42, 0x1c00
	s_addc_u32 s23, s43, 0
	s_add_u32 s24, s42, 0x1d00
	s_addc_u32 s25, s43, 0
	s_add_u32 s26, s42, 0x1e00
	s_addc_u32 s27, s43, 0
	s_add_u32 s28, s42, 0x1f00
	s_addc_u32 s29, s43, 0
	s_add_u32 s34, s42, 0x2000
	s_addc_u32 s35, s43, 0
	s_add_u32 s36, s42, 0x2100
	s_addc_u32 s37, s43, 0
	s_add_u32 s38, s42, 0x2200
	s_addc_u32 s39, s43, 0
	v_readlane_b32 s41, v248, 7
	s_add_u32 s40, s42, 0x2300
	s_addc_u32 s41, s43, 0
	s_mov_b32 s46, 1
	v_mov_b32_e32 v17, 0
	s_branch .LBB0_331
